# prologue: silu(conditioning) staging with its 6 loads in flight instead of 6 serial trips
# baseline (speedup 1.0000x reference)
.LBB0_10:
	s_load_dwordx4 s[8:11], s[0:1], 0xe0
	s_load_dwordx16 s[16:31], s[0:1], 0x0
	v_mov_b32_e32 v8, v170
	s_movk_i32 s2, 0xc00
	s_waitcnt lgkmcnt(0)
	s_barrier
	s_mov_b64 s[94:95], s[10:11]
	v_cmp_gt_i32_e32 vcc, s2, v8
	s_and_saveexec_b64 s[2:3], vcc
	s_cbranch_execz .LBB0_13
	v_lshlrev_b32_e32 v1, 2, v8
	v_add_u32_e32 v2, 0x1000, v1
	global_load_dword v12, v1, s[18:19]
	global_load_dword v13, v1, s[18:19] offset:2048
	global_load_dword v14, v2, s[18:19]
	global_load_dword v15, v2, s[18:19] offset:2048
	global_load_dword v16, v1, s[22:23]
	global_load_dword v17, v1, s[22:23] offset:2048
	s_waitcnt vmcnt(0)
	v_mul_f32_e32 v9, 0xbfb8aa3b, v12
	v_exp_f32_e32 v9, v9
	s_nop 0
	v_add_f32_e32 v6, 1.0, v9
	v_rcp_f32_e32 v9, v6
	s_nop 0
	v_mul_f32_e32 v4, v12, v9
	ds_write_b32 v1, v4
	v_mul_f32_e32 v9, 0xbfb8aa3b, v13
	v_exp_f32_e32 v9, v9
	s_nop 0
	v_add_f32_e32 v6, 1.0, v9
	v_rcp_f32_e32 v9, v6
	s_nop 0
	v_mul_f32_e32 v4, v13, v9
	ds_write_b32 v1, v4 offset:2048
	v_mul_f32_e32 v9, 0xbfb8aa3b, v14
	v_exp_f32_e32 v9, v9
	s_nop 0
	v_add_f32_e32 v6, 1.0, v9
	v_rcp_f32_e32 v9, v6
	s_nop 0
	v_mul_f32_e32 v4, v14, v9
	ds_write_b32 v1, v4 offset:4096
	v_mul_f32_e32 v9, 0xbfb8aa3b, v15
	v_exp_f32_e32 v9, v9
	s_nop 0
	v_add_f32_e32 v6, 1.0, v9
	v_rcp_f32_e32 v9, v6
	s_nop 0
	v_mul_f32_e32 v4, v15, v9
	ds_write_b32 v1, v4 offset:6144
	v_mul_f32_e32 v9, 0xbfb8aa3b, v16
	v_exp_f32_e32 v9, v9
	s_nop 0
	v_add_f32_e32 v6, 1.0, v9
	v_rcp_f32_e32 v9, v6
	s_nop 0
	v_mul_f32_e32 v4, v16, v9
	ds_write_b32 v1, v4 offset:8192
	v_mul_f32_e32 v9, 0xbfb8aa3b, v17
	v_exp_f32_e32 v9, v9
	s_nop 0
	v_add_f32_e32 v6, 1.0, v9
	v_rcp_f32_e32 v9, v6
	s_nop 0
	v_mul_f32_e32 v4, v17, v9
	ds_write_b32 v1, v4 offset:10240
